# attention pass 2: first-half softmax exps interleaved with the second-half QK MFMAs (MFMA shadow filling)
# baseline (speedup 1.0000x reference)
.LBB0_131:
	global_load_dwordx4 v[88:91], v[108:109], off
	global_load_dwordx4 v[92:95], v[108:109], off offset:-16
	global_load_dwordx4 v[96:99], v[106:107], off
	global_load_dwordx4 v[100:103], v[106:107], off offset:-16
	s_add_i32 s5, s4, 1
	s_bitcmp1_b32 s4, 0
	s_cselect_b32 s4, s91, 0
	v_add_u32_e32 v132, s4, v118
	ds_read_b128 v[124:127], v132
	ds_read_b128 v[128:131], v132 offset:64
	ds_read_b128 v[150:153], v132 offset:128
	ds_read_b128 v[154:157], v132 offset:192
	ds_read_b128 v[158:161], v132 offset:4608
	ds_read_b128 v[162:165], v132 offset:4672
	ds_read_b128 v[166:169], v132 offset:4736
	ds_read_b128 v[170:173], v132 offset:4800
	ds_read_b128 v[174:177], v132 offset:9216
	ds_read_b128 v[178:181], v132 offset:9280
	ds_read_b128 v[182:185], v132 offset:9344
	ds_read_b128 v[186:189], v132 offset:9408
	ds_read_b128 v[216:219], v132 offset:13824
	ds_read_b128 v[220:223], v132 offset:13888
	ds_read_b128 v[224:227], v132 offset:13952
	ds_read_b128 v[228:231], v132 offset:14016
	s_cselect_b32 s4, s57, s70
	s_waitcnt lgkmcnt(14)
	v_mfma_f32_16x16x32_bf16 v[124:127], v[124:127], v[12:15], v[16:19]
	v_mfma_f32_16x16x32_bf16 v[124:127], v[128:131], v[0:3], v[124:127]
	s_waitcnt lgkmcnt(13)
	v_mfma_f32_16x16x32_bf16 v[128:131], v[150:153], v[4:7], v[20:23]
	s_waitcnt lgkmcnt(12)
	v_mfma_f32_16x16x32_bf16 v[128:131], v[154:157], v[8:11], v[128:131]
	s_waitcnt lgkmcnt(11)
	v_mfma_f32_16x16x32_bf16 v[150:153], v[158:161], v[12:15], v[16:19]
	s_waitcnt lgkmcnt(9)
	v_mfma_f32_16x16x32_bf16 v[154:157], v[166:169], v[4:7], v[20:23]
	v_mfma_f32_16x16x32_bf16 v[150:153], v[162:165], v[0:3], v[150:153]
	s_waitcnt lgkmcnt(8)
	v_mfma_f32_16x16x32_bf16 v[154:157], v[170:173], v[8:11], v[154:157]
	s_waitcnt lgkmcnt(7)
	v_mfma_f32_16x16x32_bf16 v[158:161], v[174:177], v[12:15], v[16:19]
	v_exp_f32_e32 v191, v124
	v_exp_f32_e32 v190, v128
	s_waitcnt lgkmcnt(5)
	v_mfma_f32_16x16x32_bf16 v[162:165], v[182:185], v[4:7], v[20:23]
	v_exp_f32_e32 v241, v125
	v_exp_f32_e32 v240, v129
	s_waitcnt lgkmcnt(3)
	v_mfma_f32_16x16x32_bf16 v[166:169], v[216:219], v[12:15], v[16:19]
	v_exp_f32_e32 v243, v126
	v_exp_f32_e32 v242, v130
	s_waitcnt lgkmcnt(1)
	v_mfma_f32_16x16x32_bf16 v[170:173], v[224:227], v[4:7], v[20:23]
	v_exp_f32_e32 v245, v127
	v_exp_f32_e32 v244, v131
	v_mfma_f32_16x16x32_bf16 v[158:161], v[178:181], v[0:3], v[158:161]
	v_exp_f32_e32 v247, v150
	v_exp_f32_e32 v246, v154
	v_mfma_f32_16x16x32_bf16 v[162:165], v[186:189], v[8:11], v[162:165]
	v_exp_f32_e32 v249, v151
	v_exp_f32_e32 v248, v155
	v_mfma_f32_16x16x32_bf16 v[166:169], v[220:223], v[0:3], v[166:169]
	v_exp_f32_e32 v251, v152
	v_exp_f32_e32 v250, v156
	s_waitcnt lgkmcnt(0)
	v_mfma_f32_16x16x32_bf16 v[170:173], v[228:231], v[8:11], v[170:173]
	v_exp_f32_e32 v253, v153
	v_exp_f32_e32 v252, v157
	v_add_u32_e32 v132, s4, v120
	v_add_u32_e32 v200, v132, v121
	ds_read_b128 v[174:177], v200
	ds_read_b128 v[178:181], v200 offset:2048
	ds_read_b128 v[182:185], v200 offset:4096
	ds_read_b128 v[186:189], v200 offset:6144
	ds_read_b128 v[216:219], v200 offset:8192
	ds_read_b128 v[220:223], v200 offset:10240
	ds_read_b128 v[224:227], v200 offset:12288
	ds_read_b128 v[228:231], v200 offset:14336
	v_cvt_pk_bf16_f32 v124, v191, v241
	v_cvt_pk_bf16_f32 v125, v243, v245
	v_cvt_pk_bf16_f32 v126, v247, v249
	v_cvt_pk_bf16_f32 v127, v251, v253
	v_cvt_pk_bf16_f32 v128, v190, v240
	v_cvt_pk_bf16_f32 v129, v242, v244
	v_cvt_pk_bf16_f32 v130, v246, v248
	v_cvt_pk_bf16_f32 v131, v250, v252
	v_add_u32_e32 v132, v132, v119
	s_waitcnt lgkmcnt(7)
	v_mfma_f32_16x16x32_bf16 v[72:75], v[174:177], v[124:127], v[72:75]
	ds_read_b128 v[150:153], v132
	ds_read_b128 v[154:157], v132 offset:2048
	v_exp_f32_e32 v201, v158
	v_exp_f32_e32 v200, v162
	v_mfma_f32_16x16x32_bf16 v[84:87], v[174:177], v[128:131], v[84:87]
	v_exp_f32_e32 v203, v159
	v_exp_f32_e32 v202, v163
	v_exp_f32_e32 v163, v160
	s_waitcnt lgkmcnt(8)
	v_mfma_f32_16x16x32_bf16 v[68:71], v[178:181], v[124:127], v[68:71]
	v_exp_f32_e32 v162, v164
	v_exp_f32_e32 v164, v170
	v_exp_f32_e32 v167, v167
	v_mfma_f32_16x16x32_bf16 v[80:83], v[178:181], v[128:131], v[80:83]
	v_exp_f32_e32 v170, v172
	v_exp_f32_e32 v169, v169
	v_cvt_pk_bf16_f32 v158, v201, v203
	s_waitcnt lgkmcnt(7)
	v_mfma_f32_16x16x32_bf16 v[60:63], v[182:185], v[124:127], v[60:63]
	v_mfma_f32_16x16x32_bf16 v[76:79], v[182:185], v[128:131], v[76:79]
	ds_read_b128 v[174:177], v132 offset:4096
	ds_read_b128 v[178:181], v132 offset:6144
	ds_read_b128 v[182:185], v132 offset:8192
	ds_read_b128 v[232:235], v132 offset:10240
	s_waitcnt lgkmcnt(10)
	v_mfma_f32_16x16x32_bf16 v[56:59], v[186:189], v[124:127], v[56:59]
	v_mfma_f32_16x16x32_bf16 v[64:67], v[186:189], v[128:131], v[64:67]
	ds_read_b128 v[186:189], v132 offset:12288
	ds_read_b128 v[236:239], v132 offset:14336
	s_waitcnt lgkmcnt(11)
	v_mfma_f32_16x16x32_bf16 v[36:39], v[216:219], v[124:127], v[36:39]
	v_mfma_f32_16x16x32_bf16 v[52:55], v[216:219], v[128:131], v[52:55]
	v_exp_f32_e32 v217, v161
	v_exp_f32_e32 v216, v165
	v_exp_f32_e32 v165, v166
	s_waitcnt lgkmcnt(10)
	v_mfma_f32_16x16x32_bf16 v[32:35], v[220:223], v[124:127], v[32:35]
	v_exp_f32_e32 v166, v171
	v_exp_f32_e32 v171, v168
	v_exp_f32_e32 v168, v173
	v_mfma_f32_16x16x32_bf16 v[48:51], v[220:223], v[128:131], v[48:51]
	v_cvt_pk_bf16_f32 v159, v163, v217
	v_cvt_pk_bf16_f32 v160, v165, v167
	v_cvt_pk_bf16_f32 v161, v171, v169
	s_waitcnt lgkmcnt(9)
	v_mfma_f32_16x16x32_bf16 v[28:31], v[224:227], v[124:127], v[28:31]
	v_mfma_f32_16x16x32_bf16 v[44:47], v[224:227], v[128:131], v[44:47]
	s_waitcnt lgkmcnt(8)
	v_mfma_f32_16x16x32_bf16 v[24:27], v[228:231], v[124:127], v[24:27]
	v_cvt_pk_bf16_f32 v124, v200, v202
	v_cvt_pk_bf16_f32 v125, v162, v216
	v_cvt_pk_bf16_f32 v126, v164, v166
	v_mfma_f32_16x16x32_bf16 v[40:43], v[228:231], v[128:131], v[40:43]
	v_cvt_pk_bf16_f32 v127, v170, v168
	s_waitcnt lgkmcnt(7)
	v_mfma_f32_16x16x32_bf16 v[84:87], v[150:153], v[124:127], v[84:87]
	v_add_f32_e64 v128, v250, v252
	v_add_f32_e64 v129, v251, v253
	s_bitcmp1_b32 s5, 0
	v_pk_add_f32 v[130:131], v[170:171], v[168:169]
	s_waitcnt lgkmcnt(6)
	v_mfma_f32_16x16x32_bf16 v[80:83], v[154:157], v[124:127], v[80:83]
	s_cselect_b32 s4, s91, 0
	v_lshl_add_u64 v[106:107], v[106:107], 0, s[66:67]
	v_lshl_add_u64 v[108:109], v[108:109], 0, s[76:77]
	s_waitcnt lgkmcnt(5)
	v_mfma_f32_16x16x32_bf16 v[76:79], v[174:177], v[124:127], v[76:79]
	s_waitcnt lgkmcnt(4)
	v_mfma_f32_16x16x32_bf16 v[64:67], v[178:181], v[124:127], v[64:67]
	s_waitcnt lgkmcnt(3)
	v_mfma_f32_16x16x32_bf16 v[52:55], v[182:185], v[124:127], v[52:55]
	s_waitcnt lgkmcnt(2)
	v_mfma_f32_16x16x32_bf16 v[48:51], v[232:235], v[124:127], v[48:51]
	s_waitcnt lgkmcnt(1)
	v_mfma_f32_16x16x32_bf16 v[44:47], v[186:189], v[124:127], v[44:47]
	s_waitcnt lgkmcnt(0)
	v_mfma_f32_16x16x32_bf16 v[40:43], v[236:239], v[124:127], v[40:43]
	v_add_f32_e64 v124, v190, v240
	v_add_f32_e64 v125, v191, v241
	v_pk_add_f32 v[126:127], v[242:243], v[244:245]
	s_nop 0
	v_pk_add_f32 v[124:125], v[124:125], v[126:127]
	v_pk_add_f32 v[126:127], v[246:247], v[248:249]
	v_mfma_f32_16x16x32_bf16 v[72:75], v[150:153], v[158:161], v[72:75]
	v_add_f32_e64 v126, v126, v128
	v_add_f32_e64 v127, v127, v129
	v_pk_add_f32 v[128:129], v[162:163], v[216:217]
	v_pk_add_f32 v[124:125], v[124:125], v[126:127]
	v_pk_add_f32 v[126:127], v[200:201], v[202:203]
	v_mfma_f32_16x16x32_bf16 v[68:71], v[154:157], v[158:161], v[68:71]
	v_add_f32_e64 v126, v126, v128
	v_add_f32_e64 v127, v127, v129
	v_pk_add_f32 v[128:129], v[164:165], v[166:167]
	v_pk_add_f32 v[110:111], v[110:111], v[124:125]
	v_mfma_f32_16x16x32_bf16 v[60:63], v[174:177], v[158:161], v[60:63]
	v_add_f32_e64 v128, v128, v130
	v_add_f32_e64 v129, v129, v131
	v_add3_u32 v124, s4, v116, v117
	s_cselect_b32 s4, s57, s70
	v_mfma_f32_16x16x32_bf16 v[56:59], v[178:181], v[158:161], v[56:59]
	v_add_f32_e64 v126, v126, v128
	v_add_f32_e64 v127, v127, v129
	s_waitcnt vmcnt(2)
	ds_write_b128 v124, v[92:95]
	ds_write_b128 v124, v[88:91] offset:16
	v_add_u32_e32 v88, s4, v122
	v_mfma_f32_16x16x32_bf16 v[36:39], v[182:185], v[158:161], v[36:39]
	v_add_f32_e64 v110, v110, v126
	v_add_f32_e64 v111, v111, v127
	s_waitcnt vmcnt(0)
	ds_write_b128 v88, v[100:103]
	v_add_u32_e32 v88, s4, v123
	v_mfma_f32_16x16x32_bf16 v[32:35], v[232:235], v[158:161], v[32:35]
	s_cmp_lg_u32 s23, s5
	s_mov_b32 s4, s5
	ds_write_b128 v88, v[96:99]
	v_mfma_f32_16x16x32_bf16 v[28:31], v[186:189], v[158:161], v[28:31]
	s_waitcnt lgkmcnt(0)
	s_barrier
	v_mfma_f32_16x16x32_bf16 v[24:27], v[236:239], v[158:161], v[24:27]
	s_cbranch_scc1 .LBB0_131
	v_add_u32_e32 v116, 0, v118
	ds_read_b128 v[88:91], v116 offset:18432
	ds_read_b128 v[92:95], v116 offset:18496
	ds_read_b128 v[96:99], v116 offset:18560
	ds_read_b128 v[100:103], v116 offset:18624
	ds_read_b128 v[106:109], v116 offset:23040
	ds_read_b128 v[122:125], v116 offset:23104
	ds_read_b128 v[126:129], v116 offset:23168
	ds_read_b128 v[150:153], v116 offset:23232
	ds_read_b128 v[154:157], v116 offset:27648
	ds_read_b128 v[158:161], v116 offset:27712
	ds_read_b128 v[162:165], v116 offset:27776
	ds_read_b128 v[166:169], v116 offset:27840
	ds_read_b128 v[170:173], v116 offset:32256
	ds_read_b128 v[174:177], v116 offset:32320
	ds_read_b128 v[178:181], v116 offset:32384
	ds_read_b128 v[182:185], v116 offset:32448
	s_waitcnt lgkmcnt(14)
	v_mfma_f32_16x16x32_bf16 v[88:91], v[88:91], v[12:15], v[16:19]
	v_mfma_f32_16x16x32_bf16 v[88:91], v[92:95], v[0:3], v[88:91]
	s_waitcnt lgkmcnt(13)
	v_mfma_f32_16x16x32_bf16 v[92:95], v[96:99], v[4:7], v[20:23]
	s_waitcnt lgkmcnt(11)
	v_mfma_f32_16x16x32_bf16 v[96:99], v[106:109], v[12:15], v[16:19]
	v_mfma_f32_16x16x32_bf16 v[92:95], v[100:103], v[8:11], v[92:95]
	s_waitcnt lgkmcnt(10)
	v_mfma_f32_16x16x32_bf16 v[96:99], v[122:125], v[0:3], v[96:99]
	s_waitcnt lgkmcnt(9)
	v_mfma_f32_16x16x32_bf16 v[100:103], v[126:129], v[4:7], v[20:23]
	s_waitcnt lgkmcnt(7)
	v_mfma_f32_16x16x32_bf16 v[106:109], v[154:157], v[12:15], v[16:19]
	s_waitcnt lgkmcnt(5)
	v_mfma_f32_16x16x32_bf16 v[122:125], v[162:165], v[4:7], v[20:23]
	s_waitcnt lgkmcnt(3)
	v_mfma_f32_16x16x32_bf16 v[12:15], v[170:173], v[12:15], v[16:19]
	s_waitcnt lgkmcnt(1)
	v_mfma_f32_16x16x32_bf16 v[4:7], v[178:181], v[4:7], v[20:23]
	v_mfma_f32_16x16x32_bf16 v[100:103], v[150:153], v[8:11], v[100:103]
	v_mfma_f32_16x16x32_bf16 v[106:109], v[158:161], v[0:3], v[106:109]
	v_mfma_f32_16x16x32_bf16 v[122:125], v[166:169], v[8:11], v[122:125]
	v_mfma_f32_16x16x32_bf16 v[0:3], v[174:177], v[0:3], v[12:15]
	s_waitcnt lgkmcnt(0)
	v_mfma_f32_16x16x32_bf16 v[4:7], v[182:185], v[8:11], v[4:7]
	v_add_u32_e32 v116, 0, v120
	v_add_u32_e32 v117, v116, v121
	v_add_u32_e32 v118, 0xd000, v117
	ds_read_b128 v[8:11], v117 offset:53248
	ds_read_b128 v[12:15], v117 offset:55296
	ds_read_b128 v[16:19], v117 offset:57344
	ds_read_b128 v[20:23], v117 offset:59392
	ds_read_b128 v[126:129], v117 offset:61440
	ds_read_b128 v[150:153], v117 offset:63488
	ds_read_b128 v[154:157], v118 offset:12288
	ds_read_b128 v[158:161], v118 offset:14336
	v_exp_f32_e32 v120, v88
	v_exp_f32_e32 v130, v92
	v_exp_f32_e32 v166, v89
	v_exp_f32_e32 v168, v93
	v_exp_f32_e32 v170, v90
	v_exp_f32_e32 v172, v94
	v_exp_f32_e32 v174, v91
	v_exp_f32_e32 v176, v95
	v_exp_f32_e32 v178, v96
	v_exp_f32_e32 v180, v100
	v_exp_f32_e32 v182, v97
	v_exp_f32_e32 v184, v101
	v_exp_f32_e32 v186, v98
	v_exp_f32_e32 v188, v102
	v_exp_f32_e32 v190, v99
	v_exp_f32_e32 v200, v103
	s_nop 0
	v_cvt_pk_bf16_f32 v88, v120, v166
	s_nop 0
	v_cvt_pk_bf16_f32 v89, v170, v174
	s_nop 0
	v_cvt_pk_bf16_f32 v90, v178, v182
	s_nop 0
	v_cvt_pk_bf16_f32 v91, v186, v190
	s_nop 0
	v_cvt_pk_bf16_f32 v92, v130, v168
	s_nop 0
	v_cvt_pk_bf16_f32 v93, v172, v176
	s_nop 0
	v_cvt_pk_bf16_f32 v94, v180, v184
	s_nop 0
	v_cvt_pk_bf16_f32 v95, v188, v200
	v_add_u32_e32 v121, v116, v119
	s_waitcnt lgkmcnt(7)
	v_mfma_f32_16x16x32_bf16 v[72:75], v[8:11], v[88:91], v[72:75]
	v_add_u32_e32 v131, 0xd000, v121
	v_exp_f32_e32 v167, v107
	v_exp_f32_e32 v169, v123
	v_mfma_f32_16x16x32_bf16 v[8:11], v[8:11], v[92:95], v[84:87]
	v_exp_f32_e32 v171, v108
	v_exp_f32_e32 v173, v124
	v_exp_f32_e32 v175, v109
	s_waitcnt lgkmcnt(6)
	v_mfma_f32_16x16x32_bf16 v[68:71], v[12:15], v[88:91], v[68:71]
	v_exp_f32_e32 v177, v125
	v_exp_f32_e32 v179, v0
	v_exp_f32_e32 v181, v4
	v_mfma_f32_16x16x32_bf16 v[12:15], v[12:15], v[92:95], v[80:83]
	v_exp_f32_e32 v183, v1
	v_exp_f32_e32 v185, v5
	v_exp_f32_e32 v187, v2
	s_waitcnt lgkmcnt(5)
	v_mfma_f32_16x16x32_bf16 v[60:63], v[16:19], v[88:91], v[60:63]
	v_exp_f32_e32 v189, v6
	v_exp_f32_e32 v191, v3
	v_exp_f32_e32 v201, v7
	v_mfma_f32_16x16x32_bf16 v[16:19], v[16:19], v[92:95], v[76:79]
	s_nop 2
	ds_read_b128 v[76:79], v121 offset:53248
	ds_read_b128 v[80:83], v121 offset:55296
	ds_read_b128 v[84:87], v121 offset:57344
	ds_read_b128 v[96:99], v121 offset:59392
	ds_read_b128 v[100:103], v121 offset:61440
	ds_read_b128 v[116:119], v121 offset:63488
	s_nop 0
	v_cvt_pk_bf16_f32 v1, v171, v175
	s_waitcnt lgkmcnt(10)
	v_mfma_f32_16x16x32_bf16 v[56:59], v[20:23], v[88:91], v[56:59]
	s_nop 0
	v_cvt_pk_bf16_f32 v2, v179, v183
	s_nop 0
	v_cvt_pk_bf16_f32 v3, v187, v191
	v_mfma_f32_16x16x32_bf16 v[20:23], v[20:23], v[92:95], v[64:67]
	s_nop 2
	ds_read_b128 v[64:67], v131 offset:12288
	ds_read_b128 v[162:165], v131 offset:14336
	v_exp_f32_e32 v121, v106
	v_exp_f32_e32 v131, v122
	s_waitcnt lgkmcnt(11)
	v_mfma_f32_16x16x32_bf16 v[36:39], v[126:129], v[88:91], v[36:39]
	s_nop 0
	v_cvt_pk_bf16_f32 v0, v121, v167
	v_mfma_f32_16x16x32_bf16 v[52:55], v[126:129], v[92:95], v[52:55]
	s_waitcnt lgkmcnt(10)
	v_mfma_f32_16x16x32_bf16 v[32:35], v[150:153], v[88:91], v[32:35]
	v_mfma_f32_16x16x32_bf16 v[48:51], v[150:153], v[92:95], v[48:51]
	s_waitcnt lgkmcnt(9)
	v_mfma_f32_16x16x32_bf16 v[28:31], v[154:157], v[88:91], v[28:31]
	v_mfma_f32_16x16x32_bf16 v[4:7], v[154:157], v[92:95], v[44:47]
	s_nop 0
	v_cvt_pk_bf16_f32 v44, v131, v169
	s_nop 0
	v_cvt_pk_bf16_f32 v45, v173, v177
	s_nop 0
	v_cvt_pk_bf16_f32 v46, v181, v185
	s_waitcnt lgkmcnt(8)
	v_mfma_f32_16x16x32_bf16 v[24:27], v[158:161], v[88:91], v[24:27]
	s_nop 0
	v_cvt_pk_bf16_f32 v47, v189, v201
	v_mfma_f32_16x16x32_bf16 v[40:43], v[158:161], v[92:95], v[40:43]
	s_waitcnt lgkmcnt(7)
	v_mfma_f32_16x16x32_bf16 v[72:75], v[76:79], v[0:3], v[72:75]
	s_waitcnt lgkmcnt(0)
	s_barrier
	v_mfma_f32_16x16x32_bf16 v[8:11], v[76:79], v[44:47], v[8:11]
	v_add_f32_e64 v76, v130, v168
	v_add_f32_e64 v77, v131, v169
	v_pk_add_f32 v[78:79], v[172:173], v[176:177]
	v_mfma_f32_16x16x32_bf16 v[68:71], v[80:83], v[0:3], v[68:71]
	v_add_f32_e64 v76, v76, v78
	v_add_f32_e64 v77, v77, v79
	v_pk_add_f32 v[78:79], v[180:181], v[184:185]
	v_mfma_f32_16x16x32_bf16 v[12:15], v[80:83], v[44:47], v[12:15]
	v_add_f32_e64 v80, v188, v200
	v_add_f32_e64 v81, v189, v201
	v_pk_add_f32 v[78:79], v[78:79], v[80:81]
	v_pk_add_f32 v[80:81], v[186:187], v[190:191]
	v_pk_add_f32 v[76:77], v[76:77], v[78:79]
	v_pk_add_f32 v[78:79], v[170:171], v[174:175]
	v_add_f32_e32 v76, v110, v76
	v_add_f32_e32 v82, v76, v77
	v_pk_add_f32 v[76:77], v[120:121], v[166:167]
	v_mfma_f32_16x16x32_bf16 v[28:31], v[64:67], v[0:3], v[28:31]
	v_add_f32_e64 v76, v76, v78
	v_add_f32_e64 v77, v77, v79
	v_pk_add_f32 v[78:79], v[178:179], v[182:183]
	v_mfma_f32_16x16x32_bf16 v[64:67], v[64:67], v[44:47], v[4:7]
	s_nop 2
	v_add_f32_e64 v4, v78, v80
	v_add_f32_e64 v5, v79, v81
	v_mfma_f32_16x16x32_bf16 v[60:63], v[84:87], v[0:3], v[60:63]
	v_add_f32_e64 v4, v76, v4
	v_add_f32_e64 v5, v77, v5
	v_add_f32_e32 v4, v111, v4
	v_mfma_f32_16x16x32_bf16 v[16:19], v[84:87], v[44:47], v[16:19]
	v_mfma_f32_16x16x32_bf16 v[56:59], v[96:99], v[0:3], v[56:59]
	v_mfma_f32_16x16x32_bf16 v[20:23], v[96:99], v[44:47], v[20:23]
	v_mfma_f32_16x16x32_bf16 v[36:39], v[100:103], v[0:3], v[36:39]
	v_mfma_f32_16x16x32_bf16 v[52:55], v[100:103], v[44:47], v[52:55]
	v_mfma_f32_16x16x32_bf16 v[32:35], v[116:119], v[0:3], v[32:35]
	v_mfma_f32_16x16x32_bf16 v[48:51], v[116:119], v[44:47], v[48:51]
	v_mfma_f32_16x16x32_bf16 v[24:27], v[162:165], v[0:3], v[24:27]
	v_add_f32_e32 v0, v4, v5
	v_mfma_f32_16x16x32_bf16 v[40:43], v[162:165], v[44:47], v[40:43]
	s_setprio 0
	ds_bpermute_b32 v1, v114, v0
	ds_bpermute_b32 v2, v114, v82
	s_waitcnt lgkmcnt(1)
	v_add_f32_e32 v0, v0, v1
	s_waitcnt lgkmcnt(0)
	v_add_f32_e32 v1, v82, v2
	ds_bpermute_b32 v2, v115, v0
	ds_bpermute_b32 v3, v115, v1
	s_waitcnt lgkmcnt(1)
	v_add_f32_e32 v0, v0, v2
	v_div_scale_f32 v2, s[4:5], v0, v0, 1.0
	v_rcp_f32_e32 v4, v2
	s_waitcnt lgkmcnt(0)
	v_add_f32_e32 v1, v1, v3
	v_div_scale_f32 v3, vcc, 1.0, v0, 1.0
	v_fma_f32 v7, -v2, v4, 1.0
	v_fmac_f32_e32 v4, v7, v4
	v_div_scale_f32 v5, s[4:5], v1, v1, v113
	v_mul_f32_e32 v7, v3, v4
	v_rcp_f32_e32 v6, v5
	v_fma_f32 v44, -v2, v7, v3
	v_fmac_f32_e32 v7, v44, v4
	v_fma_f32 v2, -v2, v7, v3
	v_div_fmas_f32 v2, v2, v4, v7
	v_div_fixup_f32 v44, v2, v0, 1.0
	v_fma_f32 v0, -v5, v6, 1.0
	v_fmac_f32_e32 v6, v0, v6
	v_div_scale_f32 v0, vcc, v113, v1, v113
	v_mul_f32_e32 v2, v0, v6
	v_fma_f32 v3, -v5, v2, v0
	v_fmac_f32_e32 v2, v3, v6
	v_fma_f32 v0, -v5, v2, v0
	v_div_fmas_f32 v0, v0, v6, v2
	s_mov_b64 s[4:5], s[0:1]
	v_div_fixup_f32 v46, v0, v1, v113
	v_pk_mul_f32 v[0:1], v[8:9], v[46:47] op_sel_hi:[1,0]
	v_pk_mul_f32 v[2:3], v[10:11], v[46:47] op_sel_hi:[1,0]
	s_load_dwordx2 s[4:5], s[4:5], 0x78
	v_pk_fma_f32 v[74:75], v[74:75], v[44:45], v[2:3] op_sel_hi:[1,0,1] neg_lo:[0,0,1] neg_hi:[0,0,1]
	v_pk_fma_f32 v[72:73], v[72:73], v[44:45], v[0:1] op_sel_hi:[1,0,1] neg_lo:[0,0,1] neg_hi:[0,0,1]
	v_pk_mul_f32 v[0:1], v[12:13], v[46:47] op_sel_hi:[1,0]
	v_pk_mul_f32 v[2:3], v[14:15], v[46:47] op_sel_hi:[1,0]
	v_pk_fma_f32 v[68:69], v[68:69], v[44:45], v[0:1] op_sel_hi:[1,0,1] neg_lo:[0,0,1] neg_hi:[0,0,1]
	v_pk_fma_f32 v[70:71], v[70:71], v[44:45], v[2:3] op_sel_hi:[1,0,1] neg_lo:[0,0,1] neg_hi:[0,0,1]
	v_pk_mul_f32 v[0:1], v[16:17], v[46:47] op_sel_hi:[1,0]
	v_pk_mul_f32 v[2:3], v[18:19], v[46:47] op_sel_hi:[1,0]
	v_pk_fma_f32 v[60:61], v[60:61], v[44:45], v[0:1] op_sel_hi:[1,0,1] neg_lo:[0,0,1] neg_hi:[0,0,1]
	v_pk_fma_f32 v[16:17], v[62:63], v[44:45], v[2:3] op_sel_hi:[1,0,1] neg_lo:[0,0,1] neg_hi:[0,0,1]
	v_pk_mul_f32 v[0:1], v[20:21], v[46:47] op_sel_hi:[1,0]
	v_pk_mul_f32 v[2:3], v[22:23], v[46:47] op_sel_hi:[1,0]
	v_pk_fma_f32 v[14:15], v[56:57], v[44:45], v[0:1] op_sel_hi:[1,0,1] neg_lo:[0,0,1] neg_hi:[0,0,1]
	v_pk_fma_f32 v[12:13], v[58:59], v[44:45], v[2:3] op_sel_hi:[1,0,1] neg_lo:[0,0,1] neg_hi:[0,0,1]
	v_pk_mul_f32 v[0:1], v[52:53], v[46:47] op_sel_hi:[1,0]
	v_pk_mul_f32 v[2:3], v[54:55], v[46:47] op_sel_hi:[1,0]
	v_pk_fma_f32 v[10:11], v[36:37], v[44:45], v[0:1] op_sel_hi:[1,0,1] neg_lo:[0,0,1] neg_hi:[0,0,1]
	v_pk_fma_f32 v[8:9], v[38:39], v[44:45], v[2:3] op_sel_hi:[1,0,1] neg_lo:[0,0,1] neg_hi:[0,0,1]
	v_pk_mul_f32 v[0:1], v[48:49], v[46:47] op_sel_hi:[1,0]
	v_pk_mul_f32 v[2:3], v[50:51], v[46:47] op_sel_hi:[1,0]
	s_waitcnt lgkmcnt(0)
	s_add_u32 s4, s4, s8
	v_pk_fma_f32 v[4:5], v[34:35], v[44:45], v[2:3] op_sel_hi:[1,0,1] neg_lo:[0,0,1] neg_hi:[0,0,1]
	v_pk_fma_f32 v[6:7], v[32:33], v[44:45], v[0:1] op_sel_hi:[1,0,1] neg_lo:[0,0,1] neg_hi:[0,0,1]
	v_pk_mul_f32 v[2:3], v[64:65], v[46:47] op_sel_hi:[1,0]
	v_pk_mul_f32 v[0:1], v[66:67], v[46:47] op_sel_hi:[1,0]
	v_pk_mul_f32 v[18:19], v[40:41], v[46:47] op_sel_hi:[1,0]
	v_pk_mul_f32 v[20:21], v[42:43], v[46:47] op_sel_hi:[1,0]
	s_addc_u32 s5, s5, s9
	v_lshlrev_b32_e32 v46, 4, v105
	v_pk_fma_f32 v[0:1], v[30:31], v[44:45], v[0:1] op_sel_hi:[1,0,1] neg_lo:[0,0,1] neg_hi:[0,0,1]
	v_pk_fma_f32 v[2:3], v[28:29], v[44:45], v[2:3] op_sel_hi:[1,0,1] neg_lo:[0,0,1] neg_hi:[0,0,1]
	v_pk_fma_f32 v[50:51], v[26:27], v[44:45], v[20:21] op_sel_hi:[1,0,1] neg_lo:[0,0,1] neg_hi:[0,0,1]
	v_pk_fma_f32 v[52:53], v[24:25], v[44:45], v[18:19] op_sel_hi:[1,0,1] neg_lo:[0,0,1] neg_hi:[0,0,1]
	global_load_dwordx4 v[18:21], v46, s[4:5]
	global_load_dwordx4 v[22:25], v46, s[4:5] offset:64
	global_load_dwordx4 v[26:29], v46, s[4:5] offset:128
	global_load_dwordx4 v[30:33], v46, s[4:5] offset:192
	global_load_dwordx4 v[34:37], v46, s[4:5] offset:256
	global_load_dwordx4 v[38:41], v46, s[4:5] offset:320
	global_load_dwordx4 v[42:45], v46, s[4:5] offset:384
	s_nop 0
	global_load_dwordx4 v[46:49], v46, s[4:5] offset:448
	v_mov_b32_e32 v56, v73
	v_mov_b32_e32 v57, v69
	v_mov_b32_e32 v54, v72
	v_mov_b32_e32 v55, v68
	v_pk_mul_f32 v[56:57], v[56:57], v[56:57]
	v_mov_b32_e32 v58, v15
	v_pk_fma_f32 v[54:55], v[54:55], v[54:55], v[56:57]
	v_mov_b32_e32 v56, v74
	v_mov_b32_e32 v57, v70
	v_pk_fma_f32 v[54:55], v[56:57], v[56:57], v[54:55]
	v_mov_b32_e32 v56, v75
	v_mov_b32_e32 v57, v71
	v_mov_b32_e32 v59, v61
	v_pk_fma_f32 v[54:55], v[56:57], v[56:57], v[54:55]
	v_mov_b32_e32 v56, v14
	v_mov_b32_e32 v57, v60
	v_pk_mul_f32 v[58:59], v[58:59], v[58:59]
	v_mov_b32_e32 v62, v7
	v_pk_fma_f32 v[56:57], v[56:57], v[56:57], v[58:59]
	v_mov_b32_e32 v58, v12
	v_mov_b32_e32 v59, v16
	v_pk_fma_f32 v[56:57], v[58:59], v[58:59], v[56:57]
	v_mov_b32_e32 v58, v13
	v_mov_b32_e32 v59, v17
	v_mov_b32_e32 v63, v11
	v_pk_fma_f32 v[56:57], v[58:59], v[58:59], v[56:57]
	v_mov_b32_e32 v58, v6
	v_mov_b32_e32 v59, v10
	v_pk_mul_f32 v[62:63], v[62:63], v[62:63]
	v_mov_b32_e32 v64, v53
	v_pk_fma_f32 v[58:59], v[58:59], v[58:59], v[62:63]
	v_mov_b32_e32 v62, v4
	v_mov_b32_e32 v63, v8
	v_pk_fma_f32 v[58:59], v[62:63], v[62:63], v[58:59]
	v_mov_b32_e32 v62, v5
	v_mov_b32_e32 v63, v9
	v_mov_b32_e32 v65, v3
	v_add_f32_e32 v54, v54, v55
	v_pk_fma_f32 v[58:59], v[62:63], v[62:63], v[58:59]
	v_mov_b32_e32 v62, v52
	v_mov_b32_e32 v63, v2
	v_pk_mul_f32 v[64:65], v[64:65], v[64:65]
	v_add_f32_e32 v54, v57, v54
	v_pk_fma_f32 v[62:63], v[62:63], v[62:63], v[64:65]
	v_mov_b32_e32 v64, v50
	v_mov_b32_e32 v65, v0
	v_add_f32_e32 v54, v56, v54
	v_pk_fma_f32 v[62:63], v[64:65], v[64:65], v[62:63]
	v_mov_b32_e32 v64, v51
	v_mov_b32_e32 v65, v1
	v_add_f32_e32 v54, v59, v54
	v_pk_fma_f32 v[62:63], v[64:65], v[64:65], v[62:63]
	v_add_f32_e32 v54, v58, v54
	v_add_f32_e32 v54, v63, v54
	v_add_f32_e32 v54, v62, v54
	ds_bpermute_b32 v55, v114, v54
	v_sub_f32_e32 v56, 1.0, v112
	s_waitcnt lgkmcnt(0)
	v_add_f32_e32 v54, v54, v55
	ds_bpermute_b32 v55, v115, v54
	s_waitcnt lgkmcnt(0)
	v_add_f32_e32 v54, v54, v55
	v_fmamk_f32 v54, v54, 0x3c000000, v137
	v_mul_f32_e32 v55, 0x4b800000, v54
	v_cmp_gt_f32_e32 vcc, s94, v54
	s_nop 1
	v_cndmask_b32_e32 v54, v54, v55, vcc
	v_rsq_f32_e32 v54, v54
	s_nop 0
	v_mul_f32_e32 v55, 0x45800000, v54
	v_cndmask_b32_e32 v54, v54, v55, vcc
	v_mul_f32_e32 v54, v56, v54
	v_mov_b64_e32 v[56:57], s[12:13]
	v_mad_i64_i32 v[56:57], s[4:5], v104, s96, v[56:57]
	s_lshl_b32 s58, s22, 1
	v_pk_mul_f32 v[58:59], v[72:73], v[54:55] op_sel_hi:[1,0]
	v_lshl_add_u64 v[56:57], v[56:57], 0, s[58:59]
	v_lshlrev_b32_e32 v132, 3, v105
	v_pk_mul_f32 v[62:63], v[74:75], v[54:55] op_sel_hi:[1,0]
	s_waitcnt vmcnt(7)
	v_pk_mul_f32 v[18:19], v[18:19], v[58:59]
	v_lshl_add_u64 v[56:57], v[56:57], 0, v[132:133]
	v_pk_mul_f32 v[20:21], v[20:21], v[62:63]
	v_cvt_pk_bf16_f32 v18, v18, v19
	v_pk_mul_f32 v[2:3], v[2:3], v[54:55] op_sel_hi:[1,0]
	v_cvt_pk_bf16_f32 v19, v20, v21
	global_store_dwordx2 v[56:57], v[18:19], off
	v_pk_mul_f32 v[18:19], v[68:69], v[54:55] op_sel_hi:[1,0]
	v_pk_mul_f32 v[20:21], v[70:71], v[54:55] op_sel_hi:[1,0]
	s_waitcnt vmcnt(7)
	v_pk_mul_f32 v[18:19], v[22:23], v[18:19]
	v_pk_mul_f32 v[0:1], v[0:1], v[54:55] op_sel_hi:[1,0]
	v_pk_mul_f32 v[20:21], v[24:25], v[20:21]
	v_cvt_pk_bf16_f32 v18, v18, v19
	s_waitcnt vmcnt(2)
	v_pk_mul_f32 v[0:1], v[44:45], v[0:1]
	v_cvt_pk_bf16_f32 v19, v20, v21
	v_pk_mul_f32 v[2:3], v[42:43], v[2:3]
	global_store_dwordx2 v[56:57], v[18:19], off offset:32
	v_pk_mul_f32 v[18:19], v[60:61], v[54:55] op_sel_hi:[1,0]
	v_pk_mul_f32 v[14:15], v[14:15], v[54:55] op_sel_hi:[1,0]
	v_pk_mul_f32 v[10:11], v[10:11], v[54:55] op_sel_hi:[1,0]
	v_pk_mul_f32 v[6:7], v[6:7], v[54:55] op_sel_hi:[1,0]
	v_cvt_pk_bf16_f32 v2, v2, v3
	v_cvt_pk_bf16_f32 v3, v0, v1
	v_pk_mul_f32 v[0:1], v[52:53], v[54:55] op_sel_hi:[1,0]
	v_pk_mul_f32 v[16:17], v[16:17], v[54:55] op_sel_hi:[1,0]
	v_pk_mul_f32 v[18:19], v[26:27], v[18:19]
	v_pk_mul_f32 v[12:13], v[12:13], v[54:55] op_sel_hi:[1,0]
	v_pk_mul_f32 v[14:15], v[30:31], v[14:15]
	v_pk_mul_f32 v[8:9], v[8:9], v[54:55] op_sel_hi:[1,0]
	v_pk_mul_f32 v[10:11], v[34:35], v[10:11]
	v_pk_mul_f32 v[4:5], v[4:5], v[54:55] op_sel_hi:[1,0]
	v_pk_mul_f32 v[6:7], v[38:39], v[6:7]
	global_store_dwordx2 v[56:57], v[2:3], off offset:192
	v_pk_mul_f32 v[2:3], v[50:51], v[54:55] op_sel_hi:[1,0]
	s_waitcnt vmcnt(3)
	v_pk_mul_f32 v[0:1], v[46:47], v[0:1]
	s_mov_b64 s[4:5], 0
	v_pk_mul_f32 v[16:17], v[28:29], v[16:17]
	v_cvt_pk_bf16_f32 v18, v18, v19
	v_pk_mul_f32 v[12:13], v[32:33], v[12:13]
	v_cvt_pk_bf16_f32 v19, v16, v17
	global_store_dwordx2 v[56:57], v[18:19], off offset:64
	v_cvt_pk_bf16_f32 v14, v14, v15
	v_cvt_pk_bf16_f32 v15, v12, v13
	global_store_dwordx2 v[56:57], v[14:15], off offset:96
	v_pk_mul_f32 v[8:9], v[36:37], v[8:9]
	v_cvt_pk_bf16_f32 v10, v10, v11
	v_pk_mul_f32 v[4:5], v[40:41], v[4:5]
	v_cvt_pk_bf16_f32 v11, v8, v9
	global_store_dwordx2 v[56:57], v[10:11], off offset:128
	v_cvt_pk_bf16_f32 v6, v6, v7
	v_cvt_pk_bf16_f32 v7, v4, v5
	global_store_dwordx2 v[56:57], v[6:7], off offset:160
	v_pk_mul_f32 v[2:3], v[48:49], v[2:3]
	v_cvt_pk_bf16_f32 v0, v0, v1
	s_nop 0
	v_cvt_pk_bf16_f32 v1, v2, v3
	global_store_dwordx2 v[56:57], v[0:1], off offset:224
	s_branch .LBB0_77
